# gemm1 tail round split into half tiles over 64 WGs, tail convert loads batched
# speedup vs baseline: 1.0131x; 1.0002x over previous
.LBB0_208:
	s_cmpk_lt_i32 s2, 0x600
	s_cselect_b64 s[0:1], -1, 0
	v_writelane_b32 v254, s0, 30
	s_cmpk_lt_i32 s2, 0x300
	s_mov_b32 s51, 0x20000
	v_writelane_b32 v254, s1, 31
	s_cselect_b64 s[0:1], -1, 0
	v_writelane_b32 v254, s0, 32
	s_mov_b32 s83, 0
	s_movk_i32 s76, 0x139a
	v_writelane_b32 v254, s1, 33
	s_abs_i32 s0, s80
	v_cvt_f32_u32_e32 v0, s0
	s_lshl_b32 s1, s2, 4
	v_writelane_b32 v254, s1, 34
	s_sub_i32 s1, 0, s0
	v_rcp_iflag_f32_e32 v0, v0
	s_mov_b32 s46, 0x1600000
	s_mov_b32 s50, 0x3000000
	s_mov_b32 s47, s51
	v_mul_f32_e32 v0, 0x4f7ffffe, v0
	v_cvt_u32_f32_e32 v0, v0
	s_movk_i32 s33, 0x3000
	s_movk_i32 s85, 0x1000
	s_movk_i32 s88, 0xff
	v_readfirstlane_b32 s3, v0
	s_mul_i32 s1, s1, s3
	s_mul_hi_u32 s1, s3, s1
	s_add_i32 s3, s3, s1
	s_mul_hi_u32 s1, s3, 0x420
	s_mul_i32 s1, s1, s0
	s_sub_i32 s1, 0x420, s1
	s_sub_i32 s4, s1, s0
	s_cmp_ge_u32 s1, s0
	s_cselect_b32 s1, s4, s1
	s_sub_i32 s4, s1, s0
	s_cmp_ge_u32 s1, s0
	s_cselect_b32 s1, s4, s1
	s_lshl_b32 s1, s1, 1
	s_sub_i32 s4, s2, s1
	s_sub_i32 s5, s80, s1
	s_cmp_lt_i32 s2, s1
	s_cselect_b32 s5, 0, s5
	s_cselect_b32 s4, -1, s4
	s_cmp_eq_u32 s1, 0
	s_cselect_b32 s8, s2, s4
	s_mul_hi_u32 s1, s3, 0x180
	s_cselect_b32 s16, s80, s5
	s_cmpk_lt_u32 s8, 0x733
	s_mul_i32 s1, s1, s0
	s_cselect_b64 s[4:5], -1, 0
	s_sub_i32 s1, 0x180, s1
	s_sub_i32 s3, s1, s0
	s_cmp_ge_u32 s1, s0
	s_cselect_b32 s1, s3, s1
	s_sub_i32 s3, s1, s0
	s_cmp_ge_u32 s1, s0
	s_cselect_b32 s0, s3, s1
	s_sub_i32 s1, s2, s0
	s_sub_i32 s3, s80, s0
	s_cmp_lt_i32 s2, s0
	s_cselect_b32 s3, 0, s3
	s_cselect_b32 s1, -1, s1
	s_cmp_eq_u32 s0, 0
	s_cselect_b32 s1, s2, s1
	v_writelane_b32 v254, s4, 35
	s_cselect_b32 s18, s80, s3
	s_cmp_gt_i32 s1, -1
	v_writelane_b32 v254, s5, 36
	s_cselect_b64 s[4:5], -1, 0
	v_writelane_b32 v254, s4, 37
	s_cmpk_lt_u32 s1, 0x467
	s_movk_i32 s89, 0x4000
	v_writelane_b32 v254, s5, 38
	s_cselect_b64 s[4:5], -1, 0
	s_add_i32 s0, s1, 0x733
	v_writelane_b32 v254, s4, 39
	s_cmpk_lt_u32 s1, 0x466
	v_mbcnt_lo_u32_b32 v0, -1, 0
	v_writelane_b32 v254, s5, 40
	s_cselect_b64 s[4:5], -1, 0
	v_writelane_b32 v254, s4, 41
	s_ashr_i32 s9, s8, 31
	s_lshl_b64 s[6:7], s[8:9], 14
	v_writelane_b32 v254, s5, 42
	s_add_i32 s4, s1, 0xb9a
	s_add_u32 s6, s6, 0x2000000
	v_writelane_b32 v254, s1, 43
	s_addc_u32 s7, s7, 0
	v_writelane_b32 v254, s6, 44
	s_ashr_i32 s17, s16, 31
	s_movk_i32 s40, 0x6000
	v_writelane_b32 v254, s7, 45
	s_lshl_b64 s[6:7], s[16:17], 14
	v_writelane_b32 v254, s6, 46
	s_mov_b32 s41, 0xc000
	s_movk_i32 s43, 0x210
	v_writelane_b32 v254, s7, 47
	s_mov_b32 s6, s8
	v_writelane_b32 v254, s6, 48
	v_mov_b32_e32 v16, 0
	s_movk_i32 s59, 0x2c00
	v_writelane_b32 v254, s7, 49
	s_lshl_b64 s[6:7], s[8:9], 16
	v_readlane_b32 s8, v254, 19
	v_readlane_b32 s9, v254, 20
	s_add_u32 s1, s8, s6
	s_addc_u32 s3, s9, s7
	s_add_u32 s6, s1, 0x8000040
	s_addc_u32 s7, s3, 0
	v_readlane_b32 s10, v254, 21
	v_readlane_b32 s11, v254, 22
	v_readlane_b32 s12, v254, 23
	v_readlane_b32 s13, v254, 24
	v_readlane_b32 s14, v254, 25
	v_readlane_b32 s15, v254, 26
	v_writelane_b32 v254, s6, 50
	s_add_i32 s1, s2, 0xffffff00
	s_lshl_b64 s[68:69], s[16:17], 16
	v_writelane_b32 v254, s7, 51
	s_mov_b32 s6, s16
	v_writelane_b32 v254, s6, 52
	s_movk_i32 s3, 0x2000
	s_mov_b32 s54, 0x800000
	v_writelane_b32 v254, s7, 53
	s_mov_b32 s6, s2
	v_writelane_b32 v254, s6, 54
	s_mov_b32 s55, s51
	v_mov_b32_e32 v186, 0x3727c5ac
	v_writelane_b32 v254, s7, 55
	v_writelane_b32 v254, s1, 56
	s_ashr_i32 s1, s0, 31
	s_lshl_b64 s[6:7], s[0:1], 14
	s_add_u32 s6, s6, 0x2000000
	s_addc_u32 s7, s7, 0
	v_writelane_b32 v254, s6, 57
	s_ashr_i32 s19, s18, 31
	s_lshl_b64 s[0:1], s[0:1], 16
	v_writelane_b32 v254, s7, 58
	s_lshl_b64 s[6:7], s[18:19], 14
	s_add_u32 s0, s8, s0
	s_addc_u32 s1, s9, s1
	v_writelane_b32 v254, s6, 59
	s_add_u32 s0, s0, 0x8000040
	s_addc_u32 s1, s1, 0
	v_writelane_b32 v254, s7, 60
	v_writelane_b32 v254, s0, 61
	s_ashr_i32 s73, s72, 31
	s_ashr_i32 s5, s4, 31
	v_writelane_b32 v254, s1, 62
	s_mov_b32 s0, s18
	v_writelane_b32 v254, s0, 63
	s_lshl_b64 s[70:71], s[72:73], 13
	v_mov_b32_e32 v187, 0x7f7f7f7f
	v_writelane_b32 v255, s1, 0
	s_lshl_b64 s[0:1], s[18:19], 16
	v_writelane_b32 v255, s0, 1
	v_mov_b32_e32 v188, 0x3ba10414
	v_mbcnt_hi_u32_b32 v191, -1, v0
	v_writelane_b32 v255, s1, 2
	s_lshl_b64 s[0:1], s[72:73], 12
	v_writelane_b32 v255, s0, 3
	s_movk_i32 s73, 0xf33
	v_mov_b64_e32 v[192:193], 0x17f
	v_writelane_b32 v255, s1, 4
	s_lshl_b64 s[0:1], s[4:5], 14
	s_add_u32 s0, s0, 0x2000000
	s_addc_u32 s1, s1, 0
	v_writelane_b32 v255, s0, 5
	v_bfrev_b32_e32 v195, 1
	v_mov_b32_e32 v194, 0xf0
	v_writelane_b32 v255, s1, 6
	s_lshl_b64 s[0:1], s[4:5], 16
	s_add_u32 s0, s8, s0
	s_addc_u32 s1, s9, s1
	s_add_u32 s0, s0, 0x8000040
	s_addc_u32 s1, s1, 0
	v_writelane_b32 v255, s0, 7
	s_add_i32 s78, 0, 0x10000
	s_add_i32 s2, 0, 0x18000
	v_writelane_b32 v255, s1, 8
	s_add_i32 s0, 0, 0x23fc0
	v_writelane_b32 v255, s0, 9
	s_add_i32 s0, 0, 0x23fc4
	v_writelane_b32 v255, s0, 10
	s_add_i32 s0, 0, 0x8800
	v_writelane_b32 v255, s0, 11
	s_add_i32 s0, 0, 0x89b0
	v_writelane_b32 v255, s0, 12
	s_add_i32 s0, 0, 0x11210
	v_writelane_b32 v255, s0, 13
	s_mov_b64 s[0:1], 0
	v_writelane_b32 v255, s0, 14
	s_add_i32 s77, 0, 0x14000
	s_add_i32 s91, 0, 0x1c000
	v_writelane_b32 v255, s1, 15
	v_writelane_b32 v255, s68, 16
	v_mov_b32_e32 v189, 0x100
	v_mov_b32_e32 v212, 0xb9c68948
	v_writelane_b32 v255, s69, 17
	v_writelane_b32 v255, s70, 18
	v_mov_b32_e32 v213, 0x7f800000
	s_movk_i32 s92, 0x120
	v_writelane_b32 v255, s71, 19
	v_writelane_b32 v255, s78, 20
	s_mov_b32 s64, 0xf149f2ca
	s_mov_b32 s65, 0x3e0293ee
	s_mov_b32 s56, 0x41000000
	s_mov_b32 s42, 0x3e38aa3b
	s_movk_i32 s58, 0x7f
	s_movk_i32 s79, 0x5000
	s_movk_i32 s57, 0x7000
	s_brev_b32 s81, -2
	s_mov_b32 s84, 0x7fffff00
	s_mov_b32 s87, 0x3e800000
	s_mov_b32 s74, 0xff00
	s_mov_b32 s75, 0xc0c0500
	s_mov_b64 s[94:95], 0x800
	s_mov_b32 s86, 0x3fd744fd
	s_mov_b32 s96, s83
	v_writelane_b32 v255, s2, 21
	s_waitcnt lgkmcnt(0)
	s_barrier
	s_branch .LBB0_212

.LBB0_215:
	s_mul_i32 s7, s60, s80
	v_readlane_b32 s0, v254, 54
	s_mul_hi_u32 s6, s60, s80
	s_add_u32 s8, s7, s0
	s_addc_u32 s9, s6, 0
	s_mov_b32 s100, 0
	s_mov_b32 s101, 0
	s_cmp_lg_u32 s7, 0x400
	s_cbranch_scc1 .Lg1_full
	s_cmp_gt_u32 s0, 63
	s_cbranch_scc1 .Lg1_full
	s_lshr_b32 s100, s0, 5
	s_lshl_b32 s100, s100, 7
	s_mov_b32 s101, 1
	s_and_b32 s8, s0, 31
	s_add_u32 s8, s8, 0x400
	s_mov_b32 s9, 0
.Lg1_full:
	v_mov_b64_e32 v[0:1], 0x420
	v_cmp_lt_u64_e64 s[6:7], s[8:9], v[0:1]
	v_mov_b64_e32 v[0:1], 0x41f
	v_cmp_gt_u64_e32 vcc, s[8:9], v[0:1]
	v_readlane_b32 s1, v254, 55
	s_cbranch_vccz .LBB0_217
	s_andn2_b64 vcc, exec, s[6:7]
	s_mov_b64 s[6:7], -1
	s_cbranch_vccnz .LBB0_214
	s_branch .LBB0_222

.LBB0_222:
	v_readfirstlane_b32 s6, v17
	s_lshl_b32 s6, s6, 10
	s_add_i32 s27, s6, 0
	s_add_i32 s28, s27, 0x10000
	s_lshl_b32 s9, s61, 20
	s_mov_b32 m0, s28
	s_add_i32 s29, s27, 0x12000
	buffer_load_dwordx4 v140, s[44:47], s9 offen lds
	s_mov_b32 m0, s29
	s_lshl_b32 s8, s26, 20
	s_lshl_b32 s99, s100, 12
	s_add_i32 s8, s8, s99
	buffer_load_dwordx4 v141, s[44:47], s9 offen lds
	s_mov_b32 m0, s27
	s_add_i32 s30, s27, 0x2000
	buffer_load_dwordx4 v140, s[48:51], s8 offen lds
	s_mov_b32 m0, s30
	s_add_i32 s31, s27, 0x14000
	buffer_load_dwordx4 v141, s[48:51], s8 offen lds
	s_or_b32 s6, s9, 0x80000
	s_mov_b32 m0, s31
	s_add_i32 s34, s27, 0x16000
	buffer_load_dwordx4 v140, s[44:47], s6 offen lds
	s_mov_b32 m0, s34
	s_add_i32 s35, s27, 0x4000
	buffer_load_dwordx4 v141, s[44:47], s6 offen lds
	s_or_b32 s6, s8, 0x80000
	s_mov_b32 m0, s35
	s_add_i32 s36, s27, 0x6000
	buffer_load_dwordx4 v140, s[48:51], s6 offen lds
	s_mov_b32 m0, s36
	s_nop 0
	buffer_load_dwordx4 v141, s[48:51], s6 offen lds
	s_and_saveexec_b64 s[6:7], s[4:5]
	s_cbranch_execz .LBB0_224
	s_barrier

.LBB0_225:
	ds_read_b128 v[132:135], v142
	ds_read_b128 v[136:139], v142 offset:1024
	ds_read_b128 v[150:153], v142 offset:2048
	ds_read_b128 v[154:157], v142 offset:3072
	s_add_i32 s69, s8, s68
	s_add_i32 s70, s69, 0x80080
	s_mov_b32 m0, s7
	ds_read_b128 v[158:161], v143
	ds_read_b128 v[162:165], v143 offset:1024
	ds_read_b128 v[166:169], v144
	ds_read_b128 v[170:173], v144 offset:1024
	ds_read_b128 v[178:181], v145
	ds_read_b128 v[214:217], v145 offset:1024
	ds_read_b128 v[218:221], v146
	ds_read_b128 v[222:225], v146 offset:1024
	buffer_load_dwordx4 v140, s[48:51], s70 offen lds
	s_mov_b32 m0, s6
	s_nop 0
	buffer_load_dwordx4 v141, s[48:51], s70 offen lds
	s_waitcnt lgkmcnt(8)
	s_barrier
	s_waitcnt lgkmcnt(0)
	s_setprio 1
	s_waitcnt lgkmcnt(0)
	v_mfma_f32_16x16x32_bf16 v[126:129], v[132:135], v[158:161], v[126:129]
	v_mfma_f32_16x16x32_bf16 v[122:125], v[150:153], v[158:161], v[122:125]
	v_mfma_f32_16x16x32_bf16 v[118:121], v[132:135], v[166:169], v[118:121]
	v_mfma_f32_16x16x32_bf16 v[114:117], v[150:153], v[166:169], v[114:117]
	v_mfma_f32_16x16x32_bf16 v[110:113], v[132:135], v[178:181], v[110:113]
	v_mfma_f32_16x16x32_bf16 v[106:109], v[150:153], v[178:181], v[106:109]
	v_mfma_f32_16x16x32_bf16 v[102:105], v[132:135], v[218:221], v[102:105]
	v_mfma_f32_16x16x32_bf16 v[98:101], v[150:153], v[218:221], v[98:101]
	v_mfma_f32_16x16x32_bf16 v[126:129], v[136:139], v[162:165], v[126:129]
	v_mfma_f32_16x16x32_bf16 v[122:125], v[154:157], v[162:165], v[122:125]
	v_mfma_f32_16x16x32_bf16 v[118:121], v[136:139], v[170:173], v[118:121]
	v_mfma_f32_16x16x32_bf16 v[114:117], v[154:157], v[170:173], v[114:117]
	v_mfma_f32_16x16x32_bf16 v[110:113], v[136:139], v[214:217], v[110:113]
	v_mfma_f32_16x16x32_bf16 v[106:109], v[154:157], v[214:217], v[106:109]
	v_mfma_f32_16x16x32_bf16 v[102:105], v[136:139], v[222:225], v[102:105]
	v_mfma_f32_16x16x32_bf16 v[98:101], v[154:157], v[222:225], v[98:101]
	s_setprio 0
	s_barrier
	s_add_i32 s70, s9, s68
	s_add_i32 s71, s70, 0x100
	s_mov_b32 m0, s28
	ds_read_b128 v[226:229], v147
	ds_read_b128 v[230:233], v147 offset:1024
	ds_read_b128 v[234:237], v147 offset:2048
	ds_read_b128 v[238:241], v147 offset:3072
	buffer_load_dwordx4 v140, s[44:47], s71 offen lds
	s_mov_b32 m0, s29
	s_nop 0
	buffer_load_dwordx4 v141, s[44:47], s71 offen lds
	s_barrier
	s_waitcnt lgkmcnt(0)
	s_setprio 1
	s_waitcnt lgkmcnt(0)
	v_mfma_f32_16x16x32_bf16 v[94:97], v[226:229], v[158:161], v[94:97]
	v_mfma_f32_16x16x32_bf16 v[90:93], v[234:237], v[158:161], v[90:93]
	v_mfma_f32_16x16x32_bf16 v[86:89], v[226:229], v[166:169], v[86:89]
	v_mfma_f32_16x16x32_bf16 v[82:85], v[234:237], v[166:169], v[82:85]
	v_mfma_f32_16x16x32_bf16 v[78:81], v[226:229], v[178:181], v[78:81]
	v_mfma_f32_16x16x32_bf16 v[74:77], v[234:237], v[178:181], v[74:77]
	v_mfma_f32_16x16x32_bf16 v[70:73], v[226:229], v[218:221], v[70:73]
	v_mfma_f32_16x16x32_bf16 v[66:69], v[234:237], v[218:221], v[66:69]
	v_mfma_f32_16x16x32_bf16 v[94:97], v[230:233], v[162:165], v[94:97]
	v_mfma_f32_16x16x32_bf16 v[90:93], v[238:241], v[162:165], v[90:93]
	v_mfma_f32_16x16x32_bf16 v[86:89], v[230:233], v[170:173], v[86:89]
	v_mfma_f32_16x16x32_bf16 v[82:85], v[238:241], v[170:173], v[82:85]
	v_mfma_f32_16x16x32_bf16 v[78:81], v[230:233], v[214:217], v[78:81]
	v_mfma_f32_16x16x32_bf16 v[74:77], v[238:241], v[214:217], v[74:77]
	v_mfma_f32_16x16x32_bf16 v[70:73], v[230:233], v[222:225], v[70:73]
	v_mfma_f32_16x16x32_bf16 v[66:69], v[238:241], v[222:225], v[66:69]
	s_setprio 0
	s_add_i32 s71, s69, 0x100
	s_mov_b32 m0, s27
	s_barrier
	ds_read_b128 v[158:161], v143 offset:16384
	ds_read_b128 v[162:165], v143 offset:17408
	ds_read_b128 v[166:169], v144 offset:16384
	ds_read_b128 v[170:173], v144 offset:17408
	ds_read_b128 v[178:181], v145 offset:16384
	ds_read_b128 v[214:217], v145 offset:17408
	ds_read_b128 v[218:221], v146 offset:16384
	ds_read_b128 v[222:225], v146 offset:17408
	buffer_load_dwordx4 v140, s[48:51], s71 offen lds
	s_mov_b32 m0, s30
	s_nop 0
	buffer_load_dwordx4 v141, s[48:51], s71 offen lds
	s_barrier
	s_waitcnt lgkmcnt(0)
	s_setprio 1
	s_waitcnt lgkmcnt(0)
	s_cmp_lg_u32 s101, 0
	s_cbranch_scc1 .Lg1_sk0
	v_mfma_f32_16x16x32_bf16 v[62:65], v[132:135], v[158:161], v[62:65]
	v_mfma_f32_16x16x32_bf16 v[58:61], v[150:153], v[158:161], v[58:61]
	v_mfma_f32_16x16x32_bf16 v[54:57], v[132:135], v[166:169], v[54:57]
	v_mfma_f32_16x16x32_bf16 v[50:53], v[150:153], v[166:169], v[50:53]
	v_mfma_f32_16x16x32_bf16 v[46:49], v[132:135], v[178:181], v[46:49]
	v_mfma_f32_16x16x32_bf16 v[42:45], v[150:153], v[178:181], v[42:45]
	v_mfma_f32_16x16x32_bf16 v[38:41], v[132:135], v[218:221], v[38:41]
	v_mfma_f32_16x16x32_bf16 v[34:37], v[150:153], v[218:221], v[34:37]
	v_mfma_f32_16x16x32_bf16 v[62:65], v[136:139], v[162:165], v[62:65]
	v_mfma_f32_16x16x32_bf16 v[58:61], v[154:157], v[162:165], v[58:61]
	v_mfma_f32_16x16x32_bf16 v[54:57], v[136:139], v[170:173], v[54:57]
	v_mfma_f32_16x16x32_bf16 v[50:53], v[154:157], v[170:173], v[50:53]
	v_mfma_f32_16x16x32_bf16 v[46:49], v[136:139], v[214:217], v[46:49]
	v_mfma_f32_16x16x32_bf16 v[42:45], v[154:157], v[214:217], v[42:45]
	v_mfma_f32_16x16x32_bf16 v[38:41], v[136:139], v[222:225], v[38:41]
	v_mfma_f32_16x16x32_bf16 v[34:37], v[154:157], v[222:225], v[34:37]
.Lg1_sk0:
	s_setprio 0
	s_barrier
	s_add_i32 s71, s70, 0x80100
	s_mov_b32 m0, s31
	s_nop 0
	buffer_load_dwordx4 v140, s[44:47], s71 offen lds
	s_mov_b32 m0, s34
	s_nop 0
	buffer_load_dwordx4 v141, s[44:47], s71 offen lds
	s_waitcnt vmcnt(6)
	s_barrier
	s_setprio 1
	s_cmp_lg_u32 s101, 0
	s_cbranch_scc1 .Lg1_sk1
	v_mfma_f32_16x16x32_bf16 v[30:33], v[226:229], v[158:161], v[30:33]
	v_mfma_f32_16x16x32_bf16 v[26:29], v[234:237], v[158:161], v[26:29]
	v_mfma_f32_16x16x32_bf16 v[22:25], v[226:229], v[166:169], v[22:25]
	v_mfma_f32_16x16x32_bf16 v[18:21], v[234:237], v[166:169], v[18:21]
	v_mfma_f32_16x16x32_bf16 v[12:15], v[226:229], v[178:181], v[12:15]
	v_mfma_f32_16x16x32_bf16 v[8:11], v[234:237], v[178:181], v[8:11]
	v_mfma_f32_16x16x32_bf16 v[4:7], v[226:229], v[218:221], v[4:7]
	v_mfma_f32_16x16x32_bf16 v[0:3], v[234:237], v[218:221], v[0:3]
	v_mfma_f32_16x16x32_bf16 v[30:33], v[230:233], v[162:165], v[30:33]
	v_mfma_f32_16x16x32_bf16 v[26:29], v[238:241], v[162:165], v[26:29]
	v_mfma_f32_16x16x32_bf16 v[22:25], v[230:233], v[170:173], v[22:25]
	v_mfma_f32_16x16x32_bf16 v[18:21], v[238:241], v[170:173], v[18:21]
	v_mfma_f32_16x16x32_bf16 v[12:15], v[230:233], v[214:217], v[12:15]
	v_mfma_f32_16x16x32_bf16 v[8:11], v[238:241], v[214:217], v[8:11]
	v_mfma_f32_16x16x32_bf16 v[4:7], v[230:233], v[222:225], v[4:7]
	v_mfma_f32_16x16x32_bf16 v[0:3], v[238:241], v[222:225], v[0:3]
.Lg1_sk1:
	s_setprio 0
	s_barrier
	ds_read_b128 v[132:135], v148
	ds_read_b128 v[136:139], v148 offset:1024
	ds_read_b128 v[150:153], v148 offset:2048
	ds_read_b128 v[154:157], v148 offset:3072
	s_add_i32 s71, s69, 0x80100
	s_mov_b32 m0, s35
	ds_read_b128 v[158:161], v143 offset:32768
	ds_read_b128 v[162:165], v143 offset:33792
	ds_read_b128 v[166:169], v144 offset:32768
	ds_read_b128 v[170:173], v144 offset:33792
	ds_read_b128 v[178:181], v145 offset:32768
	ds_read_b128 v[214:217], v145 offset:33792
	ds_read_b128 v[218:221], v146 offset:32768
	ds_read_b128 v[222:225], v146 offset:33792
	buffer_load_dwordx4 v140, s[48:51], s71 offen lds
	s_mov_b32 m0, s36
	s_nop 0
	buffer_load_dwordx4 v141, s[48:51], s71 offen lds
	s_waitcnt lgkmcnt(8)
	s_barrier
	s_waitcnt lgkmcnt(0)
	s_setprio 1
	s_waitcnt lgkmcnt(0)
	v_mfma_f32_16x16x32_bf16 v[126:129], v[132:135], v[158:161], v[126:129]
	v_mfma_f32_16x16x32_bf16 v[122:125], v[150:153], v[158:161], v[122:125]
	v_mfma_f32_16x16x32_bf16 v[118:121], v[132:135], v[166:169], v[118:121]
	v_mfma_f32_16x16x32_bf16 v[114:117], v[150:153], v[166:169], v[114:117]
	v_mfma_f32_16x16x32_bf16 v[110:113], v[132:135], v[178:181], v[110:113]
	v_mfma_f32_16x16x32_bf16 v[106:109], v[150:153], v[178:181], v[106:109]
	v_mfma_f32_16x16x32_bf16 v[102:105], v[132:135], v[218:221], v[102:105]
	v_mfma_f32_16x16x32_bf16 v[98:101], v[150:153], v[218:221], v[98:101]
	v_mfma_f32_16x16x32_bf16 v[126:129], v[136:139], v[162:165], v[126:129]
	v_mfma_f32_16x16x32_bf16 v[122:125], v[154:157], v[162:165], v[122:125]
	v_mfma_f32_16x16x32_bf16 v[118:121], v[136:139], v[170:173], v[118:121]
	v_mfma_f32_16x16x32_bf16 v[114:117], v[154:157], v[170:173], v[114:117]
	v_mfma_f32_16x16x32_bf16 v[110:113], v[136:139], v[214:217], v[110:113]
	v_mfma_f32_16x16x32_bf16 v[106:109], v[154:157], v[214:217], v[106:109]
	v_mfma_f32_16x16x32_bf16 v[102:105], v[136:139], v[222:225], v[102:105]
	v_mfma_f32_16x16x32_bf16 v[98:101], v[154:157], v[222:225], v[98:101]
	s_setprio 0
	s_barrier
	s_add_i32 s71, s70, 0x180
	s_mov_b32 m0, s37
	ds_read_b128 v[226:229], v149
	ds_read_b128 v[230:233], v149 offset:1024
	ds_read_b128 v[234:237], v149 offset:2048
	ds_read_b128 v[238:241], v149 offset:3072
	buffer_load_dwordx4 v140, s[44:47], s71 offen lds
	s_mov_b32 m0, s38
	s_nop 0
	buffer_load_dwordx4 v141, s[44:47], s71 offen lds
	s_barrier
	s_waitcnt lgkmcnt(0)
	s_setprio 1
	s_waitcnt lgkmcnt(0)
	v_mfma_f32_16x16x32_bf16 v[94:97], v[226:229], v[158:161], v[94:97]
	v_mfma_f32_16x16x32_bf16 v[90:93], v[234:237], v[158:161], v[90:93]
	v_mfma_f32_16x16x32_bf16 v[86:89], v[226:229], v[166:169], v[86:89]
	v_mfma_f32_16x16x32_bf16 v[82:85], v[234:237], v[166:169], v[82:85]
	v_mfma_f32_16x16x32_bf16 v[78:81], v[226:229], v[178:181], v[78:81]
	v_mfma_f32_16x16x32_bf16 v[74:77], v[234:237], v[178:181], v[74:77]
	v_mfma_f32_16x16x32_bf16 v[70:73], v[226:229], v[218:221], v[70:73]
	v_mfma_f32_16x16x32_bf16 v[66:69], v[234:237], v[218:221], v[66:69]
	v_mfma_f32_16x16x32_bf16 v[94:97], v[230:233], v[162:165], v[94:97]
	v_mfma_f32_16x16x32_bf16 v[90:93], v[238:241], v[162:165], v[90:93]
	v_mfma_f32_16x16x32_bf16 v[86:89], v[230:233], v[170:173], v[86:89]
	v_mfma_f32_16x16x32_bf16 v[82:85], v[238:241], v[170:173], v[82:85]
	v_mfma_f32_16x16x32_bf16 v[78:81], v[230:233], v[214:217], v[78:81]
	v_mfma_f32_16x16x32_bf16 v[74:77], v[238:241], v[214:217], v[74:77]
	v_mfma_f32_16x16x32_bf16 v[70:73], v[230:233], v[222:225], v[70:73]
	v_mfma_f32_16x16x32_bf16 v[66:69], v[238:241], v[222:225], v[66:69]
	s_setprio 0
	s_addk_i32 s69, 0x180
	s_mov_b32 m0, s39
	s_barrier
	ds_read_b128 v[158:161], v143 offset:49152
	ds_read_b128 v[162:165], v143 offset:50176
	ds_read_b128 v[166:169], v144 offset:49152
	ds_read_b128 v[170:173], v144 offset:50176
	ds_read_b128 v[178:181], v145 offset:49152
	ds_read_b128 v[214:217], v145 offset:50176
	ds_read_b128 v[218:221], v146 offset:49152
	ds_read_b128 v[222:225], v146 offset:50176
	buffer_load_dwordx4 v140, s[48:51], s69 offen lds
	s_mov_b32 m0, s62
	s_nop 0
	buffer_load_dwordx4 v141, s[48:51], s69 offen lds
	s_barrier
	s_waitcnt lgkmcnt(0)
	s_setprio 1
	s_waitcnt lgkmcnt(0)
	s_cmp_lg_u32 s101, 0
	s_cbranch_scc1 .Lg1_sk2
	v_mfma_f32_16x16x32_bf16 v[62:65], v[132:135], v[158:161], v[62:65]
	v_mfma_f32_16x16x32_bf16 v[58:61], v[150:153], v[158:161], v[58:61]
	v_mfma_f32_16x16x32_bf16 v[54:57], v[132:135], v[166:169], v[54:57]
	v_mfma_f32_16x16x32_bf16 v[50:53], v[150:153], v[166:169], v[50:53]
	v_mfma_f32_16x16x32_bf16 v[46:49], v[132:135], v[178:181], v[46:49]
	v_mfma_f32_16x16x32_bf16 v[42:45], v[150:153], v[178:181], v[42:45]
	v_mfma_f32_16x16x32_bf16 v[38:41], v[132:135], v[218:221], v[38:41]
	v_mfma_f32_16x16x32_bf16 v[34:37], v[150:153], v[218:221], v[34:37]
	v_mfma_f32_16x16x32_bf16 v[62:65], v[136:139], v[162:165], v[62:65]
	v_mfma_f32_16x16x32_bf16 v[58:61], v[154:157], v[162:165], v[58:61]
	v_mfma_f32_16x16x32_bf16 v[54:57], v[136:139], v[170:173], v[54:57]
	v_mfma_f32_16x16x32_bf16 v[50:53], v[154:157], v[170:173], v[50:53]
	v_mfma_f32_16x16x32_bf16 v[46:49], v[136:139], v[214:217], v[46:49]
	v_mfma_f32_16x16x32_bf16 v[42:45], v[154:157], v[214:217], v[42:45]
	v_mfma_f32_16x16x32_bf16 v[38:41], v[136:139], v[222:225], v[38:41]
	v_mfma_f32_16x16x32_bf16 v[34:37], v[154:157], v[222:225], v[34:37]
.Lg1_sk2:
	s_setprio 0
	s_barrier
	s_add_i32 s70, s70, 0x80180
	s_mov_b32 m0, s63
	s_nop 0
	buffer_load_dwordx4 v140, s[44:47], s70 offen lds
	s_mov_b32 m0, s66
	s_nop 0
	buffer_load_dwordx4 v141, s[44:47], s70 offen lds
	s_waitcnt vmcnt(6)
	s_barrier
	s_setprio 1
	s_cmp_lg_u32 s101, 0
	s_cbranch_scc1 .Lg1_sk3
	v_mfma_f32_16x16x32_bf16 v[30:33], v[226:229], v[158:161], v[30:33]
	v_mfma_f32_16x16x32_bf16 v[26:29], v[234:237], v[158:161], v[26:29]
	v_mfma_f32_16x16x32_bf16 v[22:25], v[226:229], v[166:169], v[22:25]
	v_mfma_f32_16x16x32_bf16 v[18:21], v[234:237], v[166:169], v[18:21]
	v_mfma_f32_16x16x32_bf16 v[12:15], v[226:229], v[178:181], v[12:15]
	v_mfma_f32_16x16x32_bf16 v[8:11], v[234:237], v[178:181], v[8:11]
	v_mfma_f32_16x16x32_bf16 v[4:7], v[226:229], v[218:221], v[4:7]
	v_mfma_f32_16x16x32_bf16 v[0:3], v[234:237], v[218:221], v[0:3]
	v_mfma_f32_16x16x32_bf16 v[30:33], v[230:233], v[162:165], v[30:33]
	v_mfma_f32_16x16x32_bf16 v[26:29], v[238:241], v[162:165], v[26:29]
	v_mfma_f32_16x16x32_bf16 v[22:25], v[230:233], v[170:173], v[22:25]
	v_mfma_f32_16x16x32_bf16 v[18:21], v[238:241], v[170:173], v[18:21]
	v_mfma_f32_16x16x32_bf16 v[12:15], v[230:233], v[214:217], v[12:15]
	v_mfma_f32_16x16x32_bf16 v[8:11], v[238:241], v[214:217], v[8:11]
	v_mfma_f32_16x16x32_bf16 v[4:7], v[230:233], v[222:225], v[4:7]
	v_mfma_f32_16x16x32_bf16 v[0:3], v[238:241], v[222:225], v[0:3]
.Lg1_sk3:
	s_setprio 0
	s_add_i32 s67, s67, 2
	s_addk_i32 s68, 0x100
	s_cmp_lt_u32 s67, 28
	s_barrier
	s_cbranch_scc1 .LBB0_225
	v_mov_b32_e32 v150, v130
	s_or_b32 s8, s8, 0x80f80
	v_and_b32_e32 v158, 15, v150
	v_bfe_u32 v132, v150, 4, 2
	v_lshlrev_b32_e32 v134, 2, v150
	v_bfe_u32 v152, v150, 6, 2
	v_lshlrev_b32_e32 v151, 4, v132
	v_lshlrev_b32_e32 v133, 6, v158
	v_and_b32_e32 v139, 32, v134
	v_lshlrev_b32_e32 v138, 12, v152
	v_bitop3_b32 v153, v151, v139, v133 bitop3:0x36
	v_add3_u32 v133, s78, v153, v138
	ds_read_b128 v[134:137], v133
	ds_read_b128 v[154:157], v133 offset:1024
	ds_read_b128 v[160:163], v133 offset:2048
	ds_read_b128 v[164:167], v133 offset:3072
	v_ashrrev_i32_e32 v133, 2, v150
	v_lshlrev_b32_e32 v172, 6, v150
	v_and_b32_e32 v133, 0xffffffc0, v133
	v_and_b32_e32 v172, 0x3c0, v172
	v_lshlrev_b32_e32 v159, 7, v133
	v_bitop3_b32 v139, v172, v139, v151 bitop3:0x36
	s_waitcnt vmcnt(0)
	v_add3_u32 v176, 0, v153, v159
	v_add3_u32 v139, 0, v139, v159
	s_mov_b32 m0, s7
	ds_read_b128 v[168:171], v176
	ds_read_b128 v[178:181], v176 offset:1024
	ds_read_b128 v[214:217], v139 offset:2048
	ds_read_b128 v[218:221], v139 offset:3072
	ds_read_b128 v[222:225], v139 offset:4096
	ds_read_b128 v[226:229], v139 offset:5120
	ds_read_b128 v[230:233], v139 offset:6144
	ds_read_b128 v[234:237], v139 offset:7168
	buffer_load_dwordx4 v140, s[48:51], s8 offen lds
	s_mov_b32 m0, s6
	s_nop 0
	buffer_load_dwordx4 v141, s[48:51], s8 offen lds
	s_barrier
	s_waitcnt lgkmcnt(0)
	s_setprio 1
	s_waitcnt lgkmcnt(0)
	v_mfma_f32_16x16x32_bf16 v[126:129], v[134:137], v[168:171], v[126:129]
	v_mfma_f32_16x16x32_bf16 v[122:125], v[160:163], v[168:171], v[122:125]
	v_mfma_f32_16x16x32_bf16 v[118:121], v[134:137], v[214:217], v[118:121]
	v_mfma_f32_16x16x32_bf16 v[114:117], v[160:163], v[214:217], v[114:117]
	v_mfma_f32_16x16x32_bf16 v[110:113], v[134:137], v[222:225], v[110:113]
	v_mfma_f32_16x16x32_bf16 v[106:109], v[160:163], v[222:225], v[106:109]
	v_mfma_f32_16x16x32_bf16 v[102:105], v[134:137], v[230:233], v[102:105]
	v_mfma_f32_16x16x32_bf16 v[98:101], v[160:163], v[230:233], v[98:101]
	v_mfma_f32_16x16x32_bf16 v[126:129], v[154:157], v[178:181], v[126:129]
	v_mfma_f32_16x16x32_bf16 v[122:125], v[164:167], v[178:181], v[122:125]
	v_mfma_f32_16x16x32_bf16 v[118:121], v[154:157], v[218:221], v[118:121]
	v_mfma_f32_16x16x32_bf16 v[114:117], v[164:167], v[218:221], v[114:117]
	v_mfma_f32_16x16x32_bf16 v[110:113], v[154:157], v[226:229], v[110:113]
	v_mfma_f32_16x16x32_bf16 v[106:109], v[164:167], v[226:229], v[106:109]
	v_mfma_f32_16x16x32_bf16 v[102:105], v[154:157], v[234:237], v[102:105]
	v_mfma_f32_16x16x32_bf16 v[98:101], v[164:167], v[234:237], v[98:101]
	s_setprio 0
	v_add3_u32 v159, s77, v153, v138
	s_barrier
	ds_read_b128 v[238:241], v159
	ds_read_b128 v[242:245], v159 offset:1024
	ds_read_b128 v[246:249], v159 offset:2048
	ds_read_b128 v[250:253], v159 offset:3072
	s_barrier
	s_waitcnt lgkmcnt(0)
	s_setprio 1
	s_waitcnt lgkmcnt(0)
	v_mfma_f32_16x16x32_bf16 v[94:97], v[238:241], v[168:171], v[94:97]
	v_mfma_f32_16x16x32_bf16 v[182:185], v[242:245], v[178:181], v[94:97]
	v_mfma_f32_16x16x32_bf16 v[90:93], v[246:249], v[168:171], v[90:93]
	v_mfma_f32_16x16x32_bf16 v[86:89], v[238:241], v[214:217], v[86:89]
	v_mfma_f32_16x16x32_bf16 v[82:85], v[246:249], v[214:217], v[82:85]
	v_mfma_f32_16x16x32_bf16 v[78:81], v[238:241], v[222:225], v[78:81]
	v_mfma_f32_16x16x32_bf16 v[74:77], v[246:249], v[222:225], v[74:77]
	v_mfma_f32_16x16x32_bf16 v[70:73], v[238:241], v[230:233], v[70:73]
	v_mfma_f32_16x16x32_bf16 v[66:69], v[246:249], v[230:233], v[66:69]
	v_mfma_f32_16x16x32_bf16 v[168:171], v[250:253], v[178:181], v[90:93]
	v_mfma_f32_16x16x32_bf16 v[178:181], v[242:245], v[218:221], v[86:89]
	v_mfma_f32_16x16x32_bf16 v[214:217], v[250:253], v[218:221], v[82:85]
	v_mfma_f32_16x16x32_bf16 v[218:221], v[242:245], v[226:229], v[78:81]
	v_mfma_f32_16x16x32_bf16 v[222:225], v[250:253], v[226:229], v[74:77]
	v_mfma_f32_16x16x32_bf16 v[226:229], v[242:245], v[234:237], v[70:73]
	v_mfma_f32_16x16x32_bf16 v[230:233], v[250:253], v[234:237], v[66:69]
	s_setprio 0
	s_barrier
	s_nop 0
	ds_read_b128 v[66:69], v176 offset:16384
	ds_read_b128 v[70:73], v176 offset:17408
	ds_read_b128 v[74:77], v139 offset:18432
	ds_read_b128 v[78:81], v139 offset:19456
	ds_read_b128 v[82:85], v139 offset:20480
	ds_read_b128 v[86:89], v139 offset:21504
	ds_read_b128 v[90:93], v139 offset:22528
	ds_read_b128 v[94:97], v139 offset:23552
	s_waitcnt vmcnt(4)
	s_barrier
	s_waitcnt lgkmcnt(0)
	s_setprio 1
	s_waitcnt lgkmcnt(0)
	s_cmp_lg_u32 s101, 0
	s_cbranch_scc1 .Lg1_sk4
	v_mfma_f32_16x16x32_bf16 v[62:65], v[134:137], v[66:69], v[62:65]
	v_mfma_f32_16x16x32_bf16 v[58:61], v[160:163], v[66:69], v[58:61]
	v_mfma_f32_16x16x32_bf16 v[54:57], v[134:137], v[74:77], v[54:57]
	v_mfma_f32_16x16x32_bf16 v[50:53], v[160:163], v[74:77], v[50:53]
	v_mfma_f32_16x16x32_bf16 v[46:49], v[134:137], v[82:85], v[46:49]
	v_mfma_f32_16x16x32_bf16 v[42:45], v[160:163], v[82:85], v[42:45]
	v_mfma_f32_16x16x32_bf16 v[38:41], v[134:137], v[90:93], v[38:41]
	v_mfma_f32_16x16x32_bf16 v[34:37], v[160:163], v[90:93], v[34:37]
	v_mfma_f32_16x16x32_bf16 v[62:65], v[154:157], v[70:73], v[62:65]
	v_mfma_f32_16x16x32_bf16 v[58:61], v[164:167], v[70:73], v[58:61]
	v_mfma_f32_16x16x32_bf16 v[54:57], v[154:157], v[78:81], v[54:57]
	v_mfma_f32_16x16x32_bf16 v[50:53], v[164:167], v[78:81], v[50:53]
	v_mfma_f32_16x16x32_bf16 v[46:49], v[154:157], v[86:89], v[46:49]
	v_mfma_f32_16x16x32_bf16 v[42:45], v[164:167], v[86:89], v[42:45]
	v_mfma_f32_16x16x32_bf16 v[38:41], v[154:157], v[94:97], v[38:41]
	v_mfma_f32_16x16x32_bf16 v[34:37], v[164:167], v[94:97], v[34:37]
	s_setprio 0
	s_setprio 1
	v_mfma_f32_16x16x32_bf16 v[30:33], v[238:241], v[66:69], v[30:33]
	v_mfma_f32_16x16x32_bf16 v[26:29], v[246:249], v[66:69], v[26:29]
	v_mfma_f32_16x16x32_bf16 v[22:25], v[238:241], v[74:77], v[22:25]
	v_mfma_f32_16x16x32_bf16 v[18:21], v[246:249], v[74:77], v[18:21]
	v_mfma_f32_16x16x32_bf16 v[12:15], v[238:241], v[82:85], v[12:15]
	v_mfma_f32_16x16x32_bf16 v[8:11], v[246:249], v[82:85], v[8:11]
	v_mfma_f32_16x16x32_bf16 v[4:7], v[238:241], v[90:93], v[4:7]
	v_mfma_f32_16x16x32_bf16 v[0:3], v[246:249], v[90:93], v[0:3]
	v_mfma_f32_16x16x32_bf16 v[134:137], v[242:245], v[70:73], v[30:33]
	v_mfma_f32_16x16x32_bf16 v[154:157], v[250:253], v[70:73], v[26:29]
	v_mfma_f32_16x16x32_bf16 v[160:163], v[242:245], v[78:81], v[22:25]
	v_mfma_f32_16x16x32_bf16 v[164:167], v[250:253], v[78:81], v[18:21]
	v_mfma_f32_16x16x32_bf16 v[234:237], v[242:245], v[86:89], v[12:15]
	v_mfma_f32_16x16x32_bf16 v[82:85], v[250:253], v[86:89], v[8:11]
	v_mfma_f32_16x16x32_bf16 v[238:241], v[242:245], v[94:97], v[4:7]
	v_mfma_f32_16x16x32_bf16 v[242:245], v[250:253], v[94:97], v[0:3]
.Lg1_sk4:
	s_setprio 0
	s_nop 1
	v_add3_u32 v0, s2, v153, v138
	s_barrier
	ds_read_b128 v[246:249], v0
	ds_read_b128 v[250:253], v0 offset:1024
	ds_read_b128 v[200:203], v0 offset:2048
	ds_read_b128 v[172:175], v0 offset:3072
	ds_read_b128 v[4:7], v176 offset:32768
	ds_read_b128 v[8:11], v176 offset:33792
	ds_read_b128 v[12:15], v139 offset:34816
	ds_read_b128 v[18:21], v139 offset:35840
	ds_read_b128 v[22:25], v139 offset:36864
	ds_read_b128 v[26:29], v139 offset:37888
	ds_read_b128 v[30:33], v139 offset:38912
	ds_read_b128 v[208:211], v139 offset:39936
	s_waitcnt vmcnt(2)
	s_barrier
	s_waitcnt lgkmcnt(0)
	s_setprio 1
	s_waitcnt lgkmcnt(0)
	v_mfma_f32_16x16x32_bf16 v[0:3], v[246:249], v[4:7], v[126:129]
	v_mfma_f32_16x16x32_bf16 v[126:129], v[250:253], v[8:11], v[0:3]
	v_mfma_f32_16x16x32_bf16 v[0:3], v[200:203], v[4:7], v[122:125]
	v_mfma_f32_16x16x32_bf16 v[122:125], v[172:175], v[8:11], v[0:3]
	v_mfma_f32_16x16x32_bf16 v[0:3], v[246:249], v[12:15], v[118:121]
	v_mfma_f32_16x16x32_bf16 v[90:93], v[250:253], v[18:21], v[0:3]
	v_mfma_f32_16x16x32_bf16 v[0:3], v[200:203], v[12:15], v[114:117]
	v_mfma_f32_16x16x32_bf16 v[94:97], v[172:175], v[18:21], v[0:3]
	v_mfma_f32_16x16x32_bf16 v[0:3], v[246:249], v[22:25], v[110:113]
	v_mfma_f32_16x16x32_bf16 v[74:77], v[250:253], v[26:29], v[0:3]
	v_mfma_f32_16x16x32_bf16 v[0:3], v[200:203], v[22:25], v[106:109]
	v_mfma_f32_16x16x32_bf16 v[86:89], v[172:175], v[26:29], v[0:3]
	v_mfma_f32_16x16x32_bf16 v[0:3], v[246:249], v[30:33], v[102:105]
	v_mfma_f32_16x16x32_bf16 v[196:199], v[250:253], v[208:211], v[0:3]
	v_mfma_f32_16x16x32_bf16 v[0:3], v[200:203], v[30:33], v[98:101]
	v_mfma_f32_16x16x32_bf16 v[78:81], v[172:175], v[208:211], v[0:3]
	s_setprio 0
	v_add3_u32 v70, s91, v153, v138
	s_barrier
	ds_read_b128 v[204:207], v70
	s_nop 2
	ds_read_b128 v[0:3], v70 offset:1024
	ds_read_b128 v[66:69], v70 offset:2048
	ds_read_b128 v[70:73], v70 offset:3072
	s_waitcnt vmcnt(0)
	s_barrier
	s_waitcnt lgkmcnt(0)
	s_setprio 1
	s_waitcnt lgkmcnt(0)
	v_mfma_f32_16x16x32_bf16 v[98:101], v[204:207], v[4:7], v[182:185]
	v_mfma_f32_16x16x32_bf16 v[4:7], v[66:69], v[4:7], v[168:171]
	v_mfma_f32_16x16x32_bf16 v[98:101], v[0:3], v[8:11], v[98:101]
	v_mfma_f32_16x16x32_bf16 v[102:105], v[70:73], v[8:11], v[4:7]
	v_mfma_f32_16x16x32_bf16 v[8:11], v[204:207], v[12:15], v[178:181]
	v_mfma_f32_16x16x32_bf16 v[12:15], v[66:69], v[12:15], v[214:217]
	v_mfma_f32_16x16x32_bf16 v[8:11], v[0:3], v[18:21], v[8:11]
	v_mfma_f32_16x16x32_bf16 v[12:15], v[70:73], v[18:21], v[12:15]
	v_mfma_f32_16x16x32_bf16 v[18:21], v[204:207], v[22:25], v[218:221]
	v_mfma_f32_16x16x32_bf16 v[22:25], v[66:69], v[22:25], v[222:225]
	v_mfma_f32_16x16x32_bf16 v[18:21], v[0:3], v[26:29], v[18:21]
	v_mfma_f32_16x16x32_bf16 v[22:25], v[70:73], v[26:29], v[22:25]
	v_mfma_f32_16x16x32_bf16 v[26:29], v[204:207], v[30:33], v[226:229]
	v_mfma_f32_16x16x32_bf16 v[30:33], v[66:69], v[30:33], v[230:233]
	v_mfma_f32_16x16x32_bf16 v[26:29], v[0:3], v[208:211], v[26:29]
	v_mfma_f32_16x16x32_bf16 v[30:33], v[70:73], v[208:211], v[30:33]
	s_setprio 0
	s_barrier
	ds_read_b128 v[168:171], v176 offset:49152
	ds_read_b128 v[178:181], v176 offset:50176
	ds_read_b128 v[208:211], v139 offset:51200
	ds_read_b128 v[214:217], v139 offset:52224
	ds_read_b128 v[218:221], v139 offset:53248
	ds_read_b128 v[222:225], v139 offset:54272
	ds_read_b128 v[226:229], v139 offset:55296
	ds_read_b128 v[230:233], v139 offset:56320
	s_barrier
	s_waitcnt lgkmcnt(0)
	s_setprio 1
	s_waitcnt lgkmcnt(0)
	s_cmp_lg_u32 s101, 0
	s_cbranch_scc1 .Lg1_sk5
	v_mfma_f32_16x16x32_bf16 v[62:65], v[246:249], v[168:171], v[62:65]
	v_mfma_f32_16x16x32_bf16 v[58:61], v[200:203], v[168:171], v[58:61]
	v_mfma_f32_16x16x32_bf16 v[54:57], v[246:249], v[208:211], v[54:57]
	v_mfma_f32_16x16x32_bf16 v[50:53], v[200:203], v[208:211], v[50:53]
	v_mfma_f32_16x16x32_bf16 v[46:49], v[246:249], v[218:221], v[46:49]
	v_mfma_f32_16x16x32_bf16 v[42:45], v[200:203], v[218:221], v[42:45]
	v_mfma_f32_16x16x32_bf16 v[38:41], v[246:249], v[226:229], v[38:41]
	v_mfma_f32_16x16x32_bf16 v[34:37], v[200:203], v[226:229], v[34:37]
	v_mfma_f32_16x16x32_bf16 v[4:7], v[250:253], v[178:181], v[62:65]
	v_mfma_f32_16x16x32_bf16 v[182:185], v[172:175], v[178:181], v[58:61]
	v_mfma_f32_16x16x32_bf16 v[114:117], v[250:253], v[214:217], v[54:57]
	v_mfma_f32_16x16x32_bf16 v[118:121], v[172:175], v[214:217], v[50:53]
	v_mfma_f32_16x16x32_bf16 v[106:109], v[250:253], v[222:225], v[46:49]
	v_mfma_f32_16x16x32_bf16 v[110:113], v[172:175], v[222:225], v[42:45]
	v_mfma_f32_16x16x32_bf16 v[246:249], v[250:253], v[230:233], v[38:41]
	v_mfma_f32_16x16x32_bf16 v[250:253], v[172:175], v[230:233], v[34:37]
	s_setprio 0
	s_setprio 1
	v_mfma_f32_16x16x32_bf16 v[34:37], v[204:207], v[168:171], v[134:137]
	v_mfma_f32_16x16x32_bf16 v[42:45], v[204:207], v[208:211], v[160:163]
	v_mfma_f32_16x16x32_bf16 v[50:53], v[204:207], v[218:221], v[234:237]
	v_mfma_f32_16x16x32_bf16 v[58:61], v[204:207], v[226:229], v[238:241]
	v_mfma_f32_16x16x32_bf16 v[34:37], v[0:3], v[178:181], v[34:37]
	v_mfma_f32_16x16x32_bf16 v[38:41], v[66:69], v[168:171], v[154:157]
	v_mfma_f32_16x16x32_bf16 v[42:45], v[0:3], v[214:217], v[42:45]
	v_mfma_f32_16x16x32_bf16 v[46:49], v[66:69], v[208:211], v[164:167]
	v_mfma_f32_16x16x32_bf16 v[50:53], v[0:3], v[222:225], v[50:53]
	v_mfma_f32_16x16x32_bf16 v[54:57], v[66:69], v[218:221], v[82:85]
	v_mfma_f32_16x16x32_bf16 v[58:61], v[0:3], v[230:233], v[58:61]
	v_mfma_f32_16x16x32_bf16 v[0:3], v[66:69], v[226:229], v[242:245]
	v_mfma_f32_16x16x32_bf16 v[38:41], v[70:73], v[178:181], v[38:41]
	v_mfma_f32_16x16x32_bf16 v[46:49], v[70:73], v[214:217], v[46:49]
	v_mfma_f32_16x16x32_bf16 v[54:57], v[70:73], v[222:225], v[54:57]
	v_mfma_f32_16x16x32_bf16 v[62:65], v[70:73], v[230:233], v[0:3]
.Lg1_sk5:
	s_setprio 0
	s_movk_i32 s0, 0x100
	v_cmp_gt_u32_e32 vcc, s0, v150
	s_barrier
	s_and_saveexec_b64 s[6:7], vcc
	s_cbranch_execz .LBB0_228
	s_barrier

.LBB0_230:
	v_readlane_b32 s68, v255, 16
	v_readlane_b32 s70, v255, 18
	s_andn2_b64 vcc, exec, s[6:7]
	s_lshl_b32 s29, s26, 8
	s_add_i32 s29, s29, s100
	v_readlane_b32 s69, v255, 17
	v_readlane_b32 s71, v255, 19
	s_cbranch_vccnz .LBB0_280
	v_or_b32_e32 v0, s29, v158
	v_add_u32_e32 v156, v0, v133
	v_bfe_u32 v157, v150, 6, 1
	v_lshrrev_b32_e32 v159, 6, v156
	v_cmp_eq_u32_e64 s[8:9], 0, v157
	v_lshlrev_b32_e32 v155, 2, v132
	s_movk_i32 s0, 0x3f0
	v_cndmask_b32_e64 v0, v158, v159, s[8:9]
	v_lshlrev_b32_e32 v0, 4, v0
	v_and_or_b32 v0, v0, s0, v155
	v_lshlrev_b32_e32 v0, 1, v0
	v_cndmask_b32_e64 v1, 0, 1, s[34:35]
	v_cmp_ne_u32_e64 s[6:7], 1, v1
	s_andn2_b64 vcc, exec, s[34:35]
	v_lshlrev_b32_e32 v160, 2, v0
	s_cbranch_vccnz .LBB0_233
	global_load_dwordx4 v[0:3], v160, s[14:15]
	global_load_dwordx4 v[66:69], v160, s[14:15] offset:16
	v_mov_b32_e32 v70, v129
	v_mov_b32_e32 v71, v125
	v_mov_b32_e32 v72, v125
	v_mov_b32_e32 v73, v129
	s_waitcnt vmcnt(0)
	v_mov_b32_e32 v132, v0
	v_mov_b32_e32 v133, v2
	v_mov_b32_e32 v2, v1
	v_pk_mul_f32 v[70:71], v[70:71], v[68:69]
	v_pk_mul_f32 v[68:69], v[72:73], v[68:69]
	v_mul_f32_e32 v0, v128, v66
	v_mul_f32_e32 v134, v124, v67
	v_mul_f32_e32 v162, v128, v67
	v_mul_f32_e32 v66, v124, v66
	v_pk_mul_f32 v[72:73], v[122:123], v[2:3]
	v_pk_mul_f32 v[164:165], v[122:123], v[132:133]
	v_mov_b32_e32 v1, v70
	v_mov_b32_e32 v135, v71
	v_mov_b32_e32 v163, v69
	v_mov_b32_e32 v67, v68
	v_pk_fma_f32 v[136:137], v[126:127], v[132:133], v[72:73] neg_lo:[0,0,1] neg_hi:[0,0,1]
	v_pk_add_f32 v[138:139], v[0:1], v[134:135] neg_lo:[0,1] neg_hi:[0,1]
	v_pk_fma_f32 v[132:133], v[126:127], v[2:3], v[164:165]
	v_pk_add_f32 v[134:135], v[162:163], v[66:67]
	s_branch .LBB0_234

.LBB0_280:
	s_mul_hi_i32 s6, s29, 0x2c00
	s_mulk_i32 s29, 0x2c00
	s_add_u32 s8, s52, s29
	s_addc_u32 s9, s53, s6
	s_ashr_i32 s29, s28, 31
	s_lshl_b64 s[6:7], s[28:29], 1
	s_add_u32 s6, s8, s6
	v_ashrrev_i32_e32 v0, 1, v150
	v_bfe_u32 v1, v150, 5, 1
	s_movk_i32 s0, 0xffe0
	v_lshlrev_b32_e32 v137, 4, v150
	s_addc_u32 s7, s9, s7
	v_and_or_b32 v136, v0, s0, v1
	v_and_b32_e32 v0, 0x1f0, v137
	v_mov_b32_e32 v1, v16
	v_add_u32_e32 v132, 0, v0
	v_lshl_add_u64 v[134:135], s[6:7], 0, v[0:1]
	s_mov_b32 s8, 0
	s_mov_b64 s[6:7], -1
	s_waitcnt vmcnt(0) lgkmcnt(0)
	s_barrier
	s_cmp_eq_u32 s101, 0
	s_cbranch_scc1 .Lg1_flush
	v_readfirstlane_b32 s99, v150
	s_cmp_gt_u32 s99, 255
	s_cbranch_scc1 .Lg1_noflush
.Lg1_flush:
.LBB0_281:
	v_or_b32_e32 v133, s8, v136
	v_mad_u64_u32 v[138:139], s[8:9], v133, s43, v[132:133]
	ds_read_b128 v[0:3], v138
	ds_read_b128 v[66:69], v138 offset:1056
	ds_read_b128 v[70:73], v138 offset:2112
	ds_read_b128 v[156:159], v138 offset:3168
	v_or_b32_e32 v155, 2, v133
	ds_read_b128 v[160:163], v138 offset:4224
	ds_read_b128 v[164:167], v138 offset:5280
	ds_read_b128 v[168:171], v138 offset:6336
	ds_read_b128 v[172:175], v138 offset:7392
	v_mad_i64_i32 v[138:139], s[8:9], v133, s59, v[134:135]
	v_or_b32_e32 v176, 4, v133
	s_waitcnt lgkmcnt(7)
	global_store_dwordx4 v[138:139], v[0:3], off nt
	v_or_b32_e32 v177, 6, v133
	v_or_b32_e32 v178, 8, v133
	v_mad_i64_i32 v[0:1], s[8:9], v155, s59, v[134:135]
	s_waitcnt lgkmcnt(6)
	global_store_dwordx4 v[0:1], v[66:69], off nt
	v_mad_i64_i32 v[0:1], s[8:9], v176, s59, v[134:135]
	s_waitcnt lgkmcnt(5)
	global_store_dwordx4 v[0:1], v[70:73], off nt
	v_mad_i64_i32 v[0:1], s[8:9], v177, s59, v[134:135]
	v_or_b32_e32 v179, 10, v133
	s_waitcnt lgkmcnt(4)
	global_store_dwordx4 v[0:1], v[156:159], off nt
	v_mad_i64_i32 v[0:1], s[8:9], v178, s59, v[134:135]
	v_or_b32_e32 v180, 12, v133
	s_waitcnt lgkmcnt(3)
	global_store_dwordx4 v[0:1], v[160:163], off nt
	v_mad_i64_i32 v[0:1], s[8:9], v179, s59, v[134:135]
	v_or_b32_e32 v181, 14, v133
	s_waitcnt lgkmcnt(2)
	global_store_dwordx4 v[0:1], v[164:167], off nt
	v_mad_i64_i32 v[0:1], s[8:9], v180, s59, v[134:135]
	s_waitcnt lgkmcnt(1)
	global_store_dwordx4 v[0:1], v[168:171], off nt
	v_mad_i64_i32 v[0:1], s[8:9], v181, s59, v[134:135]
	s_mov_b32 s8, 16
	s_and_b64 vcc, exec, s[6:7]
	s_mov_b64 s[6:7], 0
	s_waitcnt lgkmcnt(0)
	global_store_dwordx4 v[0:1], v[172:175], off nt
	s_cbranch_vccnz .LBB0_281
.Lg1_noflush:
	s_andn2_b64 vcc, exec, s[30:31]
	s_barrier
	s_cbranch_vccnz .LBB0_292
	s_mov_b64 s[8:9], -1
	s_mov_b64 s[30:31], 0
	s_cmpk_lt_i32 s27, 0x800
	s_cbranch_scc0 .LBB0_293
	s_and_b64 vcc, exec, s[8:9]
	s_cbranch_vccnz .LBB0_296

.LBB0_321:
	global_load_dwordx4 v[8:11], v[6:7], off offset:-16
	global_load_dwordx4 v[12:15], v[6:7], off offset:-32
	global_load_dwordx4 v[18:21], v[6:7], off offset:-48
	global_load_dwordx4 v[0:3], v[6:7], off offset:-64
	global_load_dwordx4 v[26:29], v[6:7], off offset:48
	global_load_dwordx4 v[30:33], v[6:7], off offset:32
	global_load_dwordx4 v[34:37], v[6:7], off offset:16
	global_load_dwordx4 v[22:25], v[6:7], off
	s_add_i32 s6, s6, s0
	s_cmpk_lt_i32 s6, 0x733
	s_waitcnt vmcnt(4)
	v_mul_f32_e32 v17, 0x42b80000, v0
	v_mul_f32_e32 v1, 0x42b80000, v1
	v_mov_b32_e32 v0, v16
	v_cvt_scalef32_pk_fp4_f32 v0, v17, v1, 1.0
	v_mul_f32_e32 v1, 0x42b80000, v2
	v_mul_f32_e32 v2, 0x42b80000, v3
	v_cvt_scalef32_pk_fp4_f32 v0, v1, v2, 1.0 op_sel:[0,0,1,0]
	v_mul_f32_e32 v1, 0x42b80000, v18
	v_mul_f32_e32 v2, 0x42b80000, v19
	v_cvt_scalef32_pk_fp4_f32 v0, v1, v2, 1.0 op_sel:[0,0,0,1]
	v_mul_f32_e32 v1, 0x42b80000, v20
	v_mul_f32_e32 v2, 0x42b80000, v21
	v_cvt_scalef32_pk_fp4_f32 v0, v1, v2, 1.0 op_sel:[0,0,1,1]
	v_mul_f32_e32 v2, 0x42b80000, v12
	v_mul_f32_e32 v3, 0x42b80000, v13
	v_mov_b32_e32 v1, v16
	v_cvt_scalef32_pk_fp4_f32 v1, v2, v3, 1.0
	v_mul_f32_e32 v2, 0x42b80000, v14
	v_mul_f32_e32 v3, 0x42b80000, v15
	v_cvt_scalef32_pk_fp4_f32 v1, v2, v3, 1.0 op_sel:[0,0,1,0]
	v_mul_f32_e32 v2, 0x42b80000, v8
	v_mul_f32_e32 v3, 0x42b80000, v9
	v_cvt_scalef32_pk_fp4_f32 v1, v2, v3, 1.0 op_sel:[0,0,0,1]
	v_mul_f32_e32 v2, 0x42b80000, v10
	v_mul_f32_e32 v3, 0x42b80000, v11
	v_cvt_scalef32_pk_fp4_f32 v1, v2, v3, 1.0 op_sel:[0,0,1,1]
	v_mov_b32_e32 v2, v16
	v_lshl_add_u64 v[6:7], v[6:7], 0, s[68:69]
	s_waitcnt vmcnt(3)
	v_mul_f32_e32 v26, 0x42b80000, v26
	s_waitcnt vmcnt(2)
	v_mul_f32_e32 v30, 0x42b80000, v30
	v_mul_f32_e32 v31, 0x42b80000, v31
	s_waitcnt vmcnt(0)
	v_mul_f32_e32 v3, 0x42b80000, v22
	v_mul_f32_e32 v17, 0x42b80000, v23
	v_cvt_scalef32_pk_fp4_f32 v2, v3, v17, 1.0
	v_mul_f32_e32 v3, 0x42b80000, v24
	v_mul_f32_e32 v17, 0x42b80000, v25
	v_cvt_scalef32_pk_fp4_f32 v2, v3, v17, 1.0 op_sel:[0,0,1,0]
	v_mul_f32_e32 v3, 0x42b80000, v34
	v_mul_f32_e32 v17, 0x42b80000, v35
	v_cvt_scalef32_pk_fp4_f32 v2, v3, v17, 1.0 op_sel:[0,0,0,1]
	v_mul_f32_e32 v3, 0x42b80000, v36
	v_mul_f32_e32 v17, 0x42b80000, v37
	v_cvt_scalef32_pk_fp4_f32 v2, v3, v17, 1.0 op_sel:[0,0,1,1]
	v_mov_b32_e32 v3, v16
	v_cvt_scalef32_pk_fp4_f32 v3, v30, v31, 1.0
	v_mul_f32_e32 v30, 0x42b80000, v32
	v_mul_f32_e32 v31, 0x42b80000, v33
	v_cvt_scalef32_pk_fp4_f32 v3, v30, v31, 1.0 op_sel:[0,0,1,0]
	v_mul_f32_e32 v27, 0x42b80000, v27
	v_cvt_scalef32_pk_fp4_f32 v3, v26, v27, 1.0 op_sel:[0,0,0,1]
	v_mul_f32_e32 v26, 0x42b80000, v28
	v_mul_f32_e32 v27, 0x42b80000, v29
	v_cvt_scalef32_pk_fp4_f32 v3, v26, v27, 1.0 op_sel:[0,0,1,1]
	v_lshrrev_b64 v[26:27], 1, v[4:5]
	v_lshl_add_u64 v[26:27], s[4:5], 0, v[26:27]
	v_lshl_add_u64 v[4:5], v[4:5], 0, s[8:9]
	global_store_dwordx4 v[26:27], v[0:3], off
	s_cbranch_scc1 .LBB0_321
